# nt cache policy on the read-once Q tile loads of the FAST attention unit prologues
# baseline (speedup 1.0000x reference)
; __device__ __forceinline__ int v_rd_base(int lane) { return ((lane & 3) << 3) | (((lane >> 2) & 3) << 6) | (((lane >> 4) & 1) << 5) | (((lane >> 5) & 1) << 8); }
; template <int MODE, bool FAST>
; __device__ __forceinline__ int attn_item(const AttnP& a, int b, int h, int blk, char* lds) {
;     ...
;     int tid = threadIdx.x; asm volatile("" : "+v"(tid));
;     const int wid = __builtin_amdgcn_readfirstlane(tid >> 6), lane = tid & 63, r32 = lane & 31, hi = lane >> 5;
;     char* V_lds = lds; char* K_lds = lds + 32768;
;     float* wsf = (float*)(lds + 65536) + wid * 64;
;     float* rpbz = (float*)(lds + 65536 + 2048);
;     float* rpbs = rpbz + 128;
;     char* Qw = lds + 70656 + wid * 8192;
;     const size_t bh = (size_t)(b * 8 + h);
;     const int qrow = 4 * blk + (wid >> 1), half = wid & 1;
;     const int qtok = MODE == 0 ? blk * 256 + wid * 32 : qrow * 64 + half * 32;
;     const int ulo = min(max(4 * blk - 4, 0), 116), r0w = min(max(qrow - 4, 0), 120);
;     {
;         const bf16_t* Qg = (MODE == 0 ? a.QA : a.QB) + (bh * SEQ + qtok) * 128;
; #pragma unroll
;         for (int i = 0; i < 8; ++i) { const int row = i * 4 + (lane >> 4), c16 = lane & 15;
;             const bf16x8 qv = *(const bf16x8*)(Qg + (size_t)row * 128 + c16 * 8);
;             *(bf16x8*)(Qw + KSWZ(row, c16 * 16)) = qv; }
;     }
;     const char* Kh = (const char*)((MODE == 0 ? a.KA : a.KB) + bh * SKV * 128);
;     const char* Vh = (const char*)((MODE == 0 ? a.VA : a.VB) + bh * SKV * 128);
;     unsigned voffK, voffV;
;     {
;         const int krow = 4 * wid + (lane >> 4), kch = (lane & 15) ^ (krow & 7);
;         voffK = (unsigned)(krow * 256 + kch * 16);
;         const int sub = 2 * wid + (lane >> 5), kk = (sub >> 2) * 8 + ((lane & 31) >> 2), cblk = sub & 3;
;         const int kreal = kk;
;         voffV = (unsigned)(kreal * 256 + (cblk * 32 + (lane & 3) * 8) * 2);
;     }
;     const int vb0 = (int)(uintptr_t)V_lds + v_rd_base(lane);
;     int koff[4];
; #pragma unroll
;     for (int i = 0; i < 4; ++i) koff[i] = r32 * 256 + (((2 * i + hi) ^ (r32 & 7)) << 4);
;     if (MODE == 1) { for (int i = tid; i < 768; i += 512) { const int k = i - 128; rpbz[i] = (k >= 0 && k < 465) ? a.rpb[h * 465 + k] * LOG2E : 0.f; } }
;     f32x16 negm0 = f32x16{}, negm1 = f32x16{};
;     if (MODE == 1 && FAST) { const int j = half * 32 + r32, c0 = min(max(j - 8, 0), 48);
; #pragma unroll
.LBB0_164:
	v_mov_b32_e32 v46, v200
	s_ashr_i32 s26, s61, 8
	v_readfirstlane_b32 s27, v46
	s_ashr_i32 s62, s27, 6
	s_lshl_b32 s4, s62, 13
	s_and_b32 s2, s61, 7
	s_add_i32 s4, s4, 0
	s_lshl_b32 s30, s26, 3
	s_and_b32 s6, s61, 0xf8
	s_add_i32 s31, s4, 0x11400
	s_or_b32 s4, s30, s2
	s_add_i32 s6, s62, s6
	s_ashr_i32 s5, s4, 31
	s_lshl_b32 s28, s6, 5
	s_and_b32 s7, s59, 7
	s_ashr_i32 s29, s28, 31
	s_lshl_b64 s[64:65], s[4:5], 21
	s_add_u32 s5, s38, s64
	s_addc_u32 s6, s39, s65
	s_lshl_b64 s[64:65], s[28:29], 8
	s_add_u32 s64, s5, s64
	v_bfe_u32 v47, v46, 4, 2
	v_and_b32_e32 v48, 15, v46
	s_addc_u32 s65, s6, s65
	v_lshlrev_b32_e32 v192, 4, v48
	v_or_b32_e32 v2, 4, v47
	v_lshl_add_u64 v[24:25], s[64:65], 0, v[192:193]
	v_lshlrev_b32_e32 v32, 8, v2
	v_mov_b32_e32 v33, v193
	v_lshlrev_b32_e32 v192, 8, v47
	v_lshl_add_u64 v[4:5], v[24:25], 0, v[32:33]
	v_or_b32_e32 v33, 12, v47
	v_or_b32_e32 v34, 0x800, v192
	v_mov_b32_e32 v35, v193
	v_lshlrev_b32_e32 v36, 8, v33
	v_mov_b32_e32 v37, v193
	v_lshl_add_u64 v[8:9], v[24:25], 0, v[34:35]
	v_lshl_add_u64 v[12:13], v[24:25], 0, v[36:37]
	v_or_b32_e32 v35, 20, v47
	v_or_b32_e32 v37, 28, v47
	v_or_b32_e32 v38, 0x1000, v192
	v_mov_b32_e32 v39, v193
	v_lshlrev_b32_e32 v40, 8, v35
	v_mov_b32_e32 v41, v193
	v_or_b32_e32 v42, 0x1800, v192
	v_mov_b32_e32 v43, v193
	v_lshlrev_b32_e32 v44, 8, v37
	v_mov_b32_e32 v45, v193
	v_lshl_add_u64 v[0:1], v[24:25], 0, v[192:193]
	v_lshl_add_u64 v[16:17], v[24:25], 0, v[38:39]
	v_lshl_add_u64 v[20:21], v[24:25], 0, v[40:41]
	v_lshl_add_u64 v[26:27], v[24:25], 0, v[42:43]
	v_lshl_add_u64 v[28:29], v[24:25], 0, v[44:45]
	global_load_dwordx4 v[0:3], v[0:1], off nt
	s_nop 0
	global_load_dwordx4 v[4:7], v[4:5], off nt
	s_nop 0
	global_load_dwordx4 v[8:11], v[8:9], off nt
	s_nop 0
	global_load_dwordx4 v[12:15], v[12:13], off nt
	s_nop 0
	global_load_dwordx4 v[16:19], v[16:17], off nt
	s_nop 0
	global_load_dwordx4 v[20:23], v[20:21], off nt
	s_nop 0
	global_load_dwordx4 v[24:27], v[26:27], off nt
	s_nop 0
	global_load_dwordx4 v[28:31], v[28:29], off nt
	v_bitop3_b32 v39, v47, v46, 15 bitop3:0x78
	v_bitop3_b32 v33, v33, v48, 7 bitop3:0x6c
	v_bitop3_b32 v37, v37, v48, 7 bitop3:0x6c
	v_bitop3_b32 v41, v47, v48, 4 bitop3:0x36
	v_lshlrev_b32_e32 v39, 4, v39
	v_bitop3_b32 v35, v35, v48, 7 bitop3:0x6c
	v_lshlrev_b32_e32 v33, 4, v33
	v_lshlrev_b32_e32 v37, 4, v37
	v_lshlrev_b32_e32 v41, 4, v41
	v_lshlrev_b32_e32 v35, 4, v35
	v_add3_u32 v33, s31, v36, v33
	v_add3_u32 v36, s31, v44, v37
	v_add3_u32 v37, s31, v192, v39
	v_and_b32_e32 v205, 31, v46
	v_bfe_u32 v204, v46, 5, 1
	v_add3_u32 v32, s31, v32, v41
	v_add3_u32 v35, s31, v40, v35
	s_lshl_b32 s5, s62, 1
	v_add3_u32 v34, s31, v34, v39
	v_add3_u32 v38, s31, v38, v39
	v_add3_u32 v39, s31, v42, v39
	s_ashr_i32 s63, s27, 4
	s_mul_i32 s64, s4, 0x210000
	s_mul_hi_i32 s6, s4, 0x210000
	s_add_u32 s4, s40, s64
	v_lshl_or_b32 v43, s62, 2, v47
	v_bitop3_b32 v45, v43, v48, 15 bitop3:0x6c
	v_lshlrev_b32_e32 v45, 4, v45
	v_and_b32_e32 v206, 63, v46
	v_mov_b32_e32 v40, v193
	v_mov_b32_e32 v41, v193
	v_mov_b32_e32 v42, v193
	v_mov_b32_e32 v44, v193
	v_mov_b32_e32 v47, v193
	v_mov_b32_e32 v48, 0
	v_mov_b32_e32 v49, v193
	v_mov_b32_e32 v50, v193
	v_mov_b32_e32 v51, v193
	v_mov_b32_e32 v52, v193
	v_mov_b32_e32 v53, v193
	s_waitcnt vmcnt(7)
	ds_write_b128 v37, v[0:3]
	s_waitcnt vmcnt(6)
	ds_write_b128 v32, v[4:7]
	s_waitcnt vmcnt(5)
	ds_write_b128 v34, v[8:11]
	s_waitcnt vmcnt(4)
	ds_write_b128 v33, v[12:15]
	s_waitcnt vmcnt(3)
	ds_write_b128 v38, v[16:19]
	s_waitcnt vmcnt(2)
	ds_write_b128 v35, v[20:23]
	s_waitcnt vmcnt(1)
	ds_write_b128 v39, v[24:27]
	s_waitcnt vmcnt(0)
	ds_write_b128 v36, v[28:31]
	v_lshlrev_b32_e32 v2, 1, v46
	v_and_b32_e32 v11, 32, v2
	v_lshlrev_b32_e32 v2, 8, v205
	v_and_b32_e32 v3, 7, v46
	v_bitop3_b32 v4, v204, v46, 7 bitop3:0x78
	v_and_or_b32 v0, s5, 2, v204
	v_lshl_or_b32 v207, v4, 4, v2
	v_bitop3_b32 v4, v204, v3, 2 bitop3:0x36
	s_addc_u32 s5, s41, s6
	s_and_b32 s65, s63, 0xfffff8
	v_bfe_u32 v8, v46, 2, 3
	v_lshl_or_b32 v208, v4, 4, v2
	v_bitop3_b32 v4, v204, v3, 4 bitop3:0x36
	v_bitop3_b32 v3, v204, v3, 6 bitop3:0x36
	s_add_u32 s64, s42, s64
	v_lshlrev_b32_e32 v1, 4, v46
	v_lshl_or_b32 v209, v4, 4, v2
	v_lshl_or_b32 v210, v3, 4, v2
	v_or_b32_e32 v2, s65, v8
	s_addc_u32 s65, s43, s6
	s_lshl_b32 s66, s62, 10
	v_lshlrev_b32_e32 v0, 6, v0
	v_and_b32_e32 v9, 48, v1
	v_lshlrev_b32_e32 v2, 8, v2
	s_add_i32 s6, s66, 0
	v_or3_b32 v0, v0, v9, v2
	v_lshl_or_b32 v2, v43, 8, v45
	v_mov_b32_e32 v3, v193
	s_add_i32 m0, s6, 0x8000
	v_and_b32_e32 v12, 0xc0, v1
	v_lshl_add_u64 v[4:5], s[4:5], 0, v[2:3]
	v_mov_b32_e32 v1, v193
	global_load_lds_dwordx4 v2, s[4:5]
	s_mov_b32 m0, s6
	v_lshl_add_u64 v[6:7], s[64:65], 0, v[0:1]
	global_load_lds_dwordx4 v0, s[64:65]
	v_lshl_add_u64 v[0:1], v[4:5], 0, s[16:17]
	s_add_i32 m0, s6, 0xa000
	v_lshlrev_b32_e32 v10, 3, v206
	global_load_lds_dwordx4 v[0:1], off
	v_lshl_add_u64 v[0:1], v[6:7], 0, s[16:17]
	s_add_i32 m0, s6, 0x2000
	s_cmp_lg_u32 0, -1
	global_load_lds_dwordx4 v[0:1], off
	v_and_b32_e32 v13, 24, v10
	s_cselect_b32 s4, 0, 0
	v_add3_u32 v1, v12, s4, v13
	s_or_b32 s4, s30, s7
	s_mul_hi_i32 s5, s4, 0x210000
	s_mul_i32 s4, s4, 0x210000
	s_add_u32 s4, s36, s4
	s_addc_u32 s5, s37, s5
	s_lshl_b32 s7, s63, 8
	s_waitcnt lgkmcnt(0)
; #define SBAR() __builtin_amdgcn_sched_barrier(0)
; template <int MODE, bool FAST>
; __device__ __forceinline__ int attn_item(const AttnP& a, int b, int h, int blk, char* lds) {
;     ...
;     bf16x8 qreg[4];
; #pragma unroll
;     for (int i = 0; i < 4; ++i) qreg[i] = *(const bf16x8*)(Qw + koff[i]);
;     asm volatile("s_waitcnt vmcnt(0) lgkmcnt(0)" ::: "memory");
;     __syncthreads();
;     ...
;             const char* Kc = K_lds + cur * 16384; const int vb = vb0 + cur * 16384;
;             bf16x8 pa[NMAP][4];
; #pragma unroll
;             for (int mp = 0; mp < NMAP; ++mp) {
;                 SBAR();
;                 f32x16 p0 = f32x16{}, p1 = f32x16{};
;                 if (MODE == 1 && FAST && t >= 4) { p0 = negm0; p1 = negm1; }
; #pragma unroll
;                 for (int d0 = 0; d0 < KD0; ++d0) { const int dd = (MODE == 0 ? mp * 4 : 0) + d0; const int off = koff[dd & 3] + (dd >> 2) * 128;
;                     const bf16x8 k0 = *(const bf16x8*)(Kc + off); const bf16x8 k1 = *(const bf16x8*)(Kc + off + 8192);
	v_add_u32_e32 v211, s31, v207
	v_add_u32_e32 v213, s31, v209
	v_and_b32_e32 v0, 0x100, v10
	s_and_b32 s7, s7, 0xfffff800
	v_add_u32_e32 v212, s31, v208
	ds_read_b128 v[160:163], v211
	ds_read_b128 v[164:167], v212
	v_add_u32_e32 v214, s31, v210
	ds_read_b128 v[168:171], v213
	ds_read_b128 v[172:175], v214
	v_add3_u32 v215, v1, v11, v0
	v_lshl_or_b32 v0, v8, 8, s7
	s_lshl_b32 s7, s62, 7
	s_and_b32 s7, s7, 0x80
	s_waitcnt vmcnt(0) lgkmcnt(0)
	v_or3_b32 v192, s66, v192, v45
	v_or_b32_e32 v0, s7, v0
	v_lshlrev_b32_e32 v1, 6, v204
	v_lshl_add_u64 v[194:195], s[4:5], 0, v[192:193]
	v_or3_b32 v192, v0, v1, v9
	v_lshl_add_u64 v[196:197], s[4:5], 0, v[192:193]
	v_bfe_u32 v2, v205, 3, 1
	v_lshl_or_b32 v207, v2, 7, v207
	v_lshl_or_b32 v208, v2, 7, v208
	v_lshl_or_b32 v209, v2, 7, v209
	v_lshl_or_b32 v210, v2, 7, v210
	s_mov_b64 s[4:5], 0
	v_mov_b32_e32 v0, 0
	v_mov_b32_e32 v1, v193
	v_mov_b32_e32 v2, v193
	v_mov_b32_e32 v4, v193
	v_mov_b32_e32 v5, v193
	v_mov_b32_e32 v6, v193
	v_mov_b32_e32 v7, v193
	v_mov_b32_e32 v8, v193
	v_mov_b32_e32 v9, v193
	v_mov_b32_e32 v10, v193
	v_mov_b32_e32 v11, v193
	v_mov_b32_e32 v12, v193
	v_mov_b32_e32 v13, v193
	v_mov_b32_e32 v14, v193
	v_mov_b32_e32 v15, v193
	v_mov_b32_e32 v16, 0
	v_mov_b32_e32 v17, v193
	v_mov_b32_e32 v18, v193
	v_mov_b32_e32 v19, v193
	v_mov_b32_e32 v20, v193
	v_mov_b32_e32 v21, v193
	v_mov_b32_e32 v22, v193
	v_mov_b32_e32 v23, v193
	v_mov_b32_e32 v24, v193
	v_mov_b32_e32 v25, v193
	v_mov_b32_e32 v26, v193
	v_mov_b32_e32 v27, v193
	v_mov_b32_e32 v28, v193
	v_mov_b32_e32 v29, v193
	v_mov_b32_e32 v30, v193
	v_mov_b32_e32 v31, v193
	v_mov_b32_e32 v32, 0
	v_mov_b32_e32 v33, v193
	v_mov_b32_e32 v34, v193
	v_mov_b32_e32 v35, v193
	v_mov_b32_e32 v36, v193
	v_mov_b32_e32 v37, v193
	v_mov_b32_e32 v38, v193
	v_mov_b32_e32 v39, v193
	v_mov_b32_e32 v43, v193
	v_mov_b32_e32 v45, v193
	v_mov_b32_e32 v46, v193
	v_mov_b32_e32 v54, v193
	v_mov_b32_e32 v55, v193
	v_mov_b32_e32 v56, v193
	v_mov_b32_e32 v57, v193
	v_mov_b32_e32 v58, v193
	v_mov_b32_e32 v59, v193
	v_mov_b32_e32 v60, v193
	v_mov_b32_e32 v61, v193
	v_mov_b32_e32 v62, v193
	v_mov_b32_e32 v63, v193
	v_mov_b32_e32 v64, 0
	v_mov_b32_e32 v65, v193
	v_mov_b32_e32 v66, v193
	v_mov_b32_e32 v67, v193
	v_mov_b32_e32 v68, v193
	v_mov_b32_e32 v69, v193
	v_mov_b32_e32 v70, v193
	v_mov_b32_e32 v71, v193
	v_mov_b32_e32 v72, v193
	v_mov_b32_e32 v73, v193
	v_mov_b32_e32 v74, v193
	v_mov_b32_e32 v75, v193
	v_mov_b32_e32 v76, v193
	v_mov_b32_e32 v77, v193
	v_mov_b32_e32 v78, v193
	v_mov_b32_e32 v79, v193
	v_mov_b32_e32 v80, 0
	v_mov_b32_e32 v81, v193
	v_mov_b32_e32 v82, v193
	v_mov_b32_e32 v83, v193
	v_mov_b32_e32 v84, v193
	v_mov_b32_e32 v85, v193
	v_mov_b32_e32 v86, v193
	v_mov_b32_e32 v87, v193
	v_mov_b32_e32 v88, v193
	v_mov_b32_e32 v89, v193
	v_mov_b32_e32 v90, v193
	v_mov_b32_e32 v91, v193
	v_mov_b32_e32 v92, v193
	v_mov_b32_e32 v93, v193
	v_mov_b32_e32 v94, v193
	v_mov_b32_e32 v95, v193
	v_mov_b32_e32 v96, 0
	v_mov_b32_e32 v97, v193
	v_mov_b32_e32 v98, v193
	v_mov_b32_e32 v99, v193
	v_mov_b32_e32 v100, v193
	v_mov_b32_e32 v101, v193
	v_mov_b32_e32 v102, v193
	v_mov_b32_e32 v103, v193
	v_mov_b32_e32 v104, v193
	v_mov_b32_e32 v105, v193
	v_mov_b32_e32 v106, v193
	v_mov_b32_e32 v107, v193
	v_mov_b32_e32 v108, v193
	v_mov_b32_e32 v109, v193
	v_mov_b32_e32 v110, v193
	v_mov_b32_e32 v111, v193
	v_mov_b32_e32 v112, 0
	v_mov_b32_e32 v113, v193
	v_mov_b32_e32 v114, v193
	v_mov_b32_e32 v115, v193
	v_mov_b32_e32 v116, v193
	v_mov_b32_e32 v117, v193
	v_mov_b32_e32 v118, v193
	v_mov_b32_e32 v119, v193
	v_mov_b32_e32 v120, v193
	v_mov_b32_e32 v121, v193
	v_mov_b32_e32 v122, v193
	v_mov_b32_e32 v123, v193
	v_mov_b32_e32 v124, v193
	v_mov_b32_e32 v125, v193
	v_mov_b32_e32 v126, v193
	v_mov_b32_e32 v127, v193
	v_mov_b32_e32 v198, 0
	v_mov_b32_e32 v199, v193
	s_waitcnt vmcnt(0) lgkmcnt(0)
	s_barrier
	s_and_b32 s7, s4, 0x4000
	v_add_u32_e32 v252, s7, v207
	v_add_u32_e32 v253, s7, v208
	ds_read_b128 v[176:179], v252 offset:32768
	ds_read_b128 v[180:183], v252 offset:40960
	ds_read_b128 v[184:187], v253 offset:32768
	ds_read_b128 v[188:191], v253 offset:40960
	v_add_u32_e32 v252, s7, v209
	v_add_u32_e32 v253, s7, v210
	ds_read_b128 v[224:227], v252 offset:32768
	ds_read_b128 v[228:231], v252 offset:40960
	ds_read_b128 v[240:243], v253 offset:32768
	ds_read_b128 v[244:247], v253 offset:40960
	s_branch .Lmy_C

; template <int MODE, bool FAST>
; __device__ __forceinline__ int attn_item(const AttnP& a, int b, int h, int blk, char* lds) {
;     ...
;     const int qrow = 4 * blk + (wid >> 1), half = wid & 1;
;     const int qtok = MODE == 0 ? blk * 256 + wid * 32 : qrow * 64 + half * 32;
;     const int ulo = min(max(4 * blk - 4, 0), 116), r0w = min(max(qrow - 4, 0), 120);
;     {
;         const bf16_t* Qg = (MODE == 0 ? a.QA : a.QB) + (bh * SEQ + qtok) * 128;
; #pragma unroll
;         for (int i = 0; i < 8; ++i) { const int row = i * 4 + (lane >> 4), c16 = lane & 15;
;             const bf16x8 qv = *(const bf16x8*)(Qg + (size_t)row * 128 + c16 * 8);
;             *(bf16x8*)(Qw + KSWZ(row, c16 * 16)) = qv; }
;     ...
;     if (MODE == 1) { for (int i = tid; i < 768; i += 512) { const int k = i - 128; rpbz[i] = (k >= 0 && k < 465) ? a.rpb[h * 465 + k] * LOG2E : 0.f; } }
.LBB0_196:
	v_mov_b32_e32 v3, v200
	s_lshr_b32 s16, s50, 1
	v_readfirstlane_b32 s15, v3
	s_ashr_i32 s1, s15, 6
	s_ashr_i32 s14, s50, 8
	s_lshl_b32 s4, s1, 13
	s_and_b32 s56, s16, 0x7c
	s_ashr_i32 s52, s15, 7
	s_and_b32 s0, s50, 7
	s_add_i32 s51, s4, 0
	s_lshl_b32 s4, s14, 3
	s_add_i32 s57, s52, s56
	s_lshl_b32 s17, s1, 5
	s_or_b32 s4, s4, s0
	s_lshl_b32 s16, s57, 6
	s_and_b32 s55, s17, 32
	s_ashr_i32 s5, s4, 31
	s_or_b32 s16, s16, s55
	s_add_i32 s51, s51, 0x11400
	s_ashr_i32 s17, s16, 31
	s_lshl_b64 s[18:19], s[4:5], 21
	s_add_u32 s5, s78, s18
	s_addc_u32 s20, s79, s19
	s_lshl_b64 s[18:19], s[16:17], 8
	s_add_u32 s18, s5, s18
	v_bfe_u32 v2, v3, 4, 2
	v_and_b32_e32 v4, 15, v3
	s_addc_u32 s19, s20, s19
	v_lshlrev_b32_e32 v0, 4, v4
	v_or_b32_e32 v8, 4, v2
	v_lshl_add_u64 v[30:31], s[18:19], 0, v[0:1]
	v_lshlrev_b32_e32 v0, 8, v2
	v_bitop3_b32 v5, v2, v3, 15 bitop3:0x78
	v_lshlrev_b32_e32 v38, 8, v8
	v_mov_b32_e32 v39, v1
	v_lshlrev_b32_e32 v5, 4, v5
	v_lshl_add_u64 v[10:11], v[30:31], 0, v[38:39]
	v_or_b32_e32 v40, 0x800, v0
	v_mov_b32_e32 v41, v1
	v_or_b32_e32 v39, 12, v2
	v_or_b32_e32 v44, 0x1000, v0
	v_mov_b32_e32 v45, v1
	v_lshl_add_u64 v[6:7], v[30:31], 0, v[0:1]
	v_add3_u32 v48, s51, v0, v5
	v_lshl_add_u64 v[14:15], v[30:31], 0, v[40:41]
	v_lshlrev_b32_e32 v42, 8, v39
	v_mov_b32_e32 v43, v1
	v_lshl_add_u64 v[22:23], v[30:31], 0, v[44:45]
	v_or_b32_e32 v41, 20, v2
	v_or_b32_e32 v0, 0x1800, v0
	v_or_b32_e32 v45, 28, v2
	v_lshl_add_u64 v[18:19], v[30:31], 0, v[42:43]
	v_lshlrev_b32_e32 v46, 8, v41
	v_mov_b32_e32 v47, v1
	v_lshl_add_u64 v[32:33], v[30:31], 0, v[0:1]
	v_add3_u32 v43, s51, v0, v5
	v_lshlrev_b32_e32 v0, 8, v45
	v_lshl_add_u64 v[26:27], v[30:31], 0, v[46:47]
	v_lshl_add_u64 v[34:35], v[30:31], 0, v[0:1]
	global_load_dwordx4 v[6:9], v[6:7], off nt
	s_nop 0
	global_load_dwordx4 v[10:13], v[10:11], off nt
	s_nop 0
	global_load_dwordx4 v[14:17], v[14:15], off nt
	s_nop 0
	global_load_dwordx4 v[18:21], v[18:19], off nt
	s_nop 0
	global_load_dwordx4 v[22:25], v[22:23], off nt
	s_nop 0
	global_load_dwordx4 v[26:29], v[26:27], off nt
	s_nop 0
	global_load_dwordx4 v[30:33], v[32:33], off nt
	s_nop 0
	global_load_dwordx4 v[34:37], v[34:35], off nt
	v_bitop3_b32 v47, v2, v4, 4 bitop3:0x36
	v_bitop3_b32 v39, v39, v4, 7 bitop3:0x6c
	v_bitop3_b32 v41, v41, v4, 7 bitop3:0x6c
	v_bitop3_b32 v45, v45, v4, 7 bitop3:0x6c
	v_lshlrev_b32_e32 v47, 4, v47
	v_lshlrev_b32_e32 v39, 4, v39
	v_lshlrev_b32_e32 v41, 4, v41
	v_lshlrev_b32_e32 v45, 4, v45
	v_cmp_gt_i32_e32 vcc, s24, v3
	v_add3_u32 v38, s51, v38, v47
	v_add3_u32 v39, s51, v42, v39
	v_add3_u32 v41, s51, v46, v41
	v_add3_u32 v40, s51, v40, v5
	v_add3_u32 v5, s51, v44, v5
	v_add3_u32 v0, s51, v0, v45
	s_waitcnt vmcnt(7)
	ds_write_b128 v48, v[6:9]
	s_waitcnt vmcnt(6)
	ds_write_b128 v38, v[10:13]
	s_waitcnt vmcnt(5)
	ds_write_b128 v40, v[14:17]
	s_waitcnt vmcnt(4)
	ds_write_b128 v39, v[18:21]
	s_waitcnt vmcnt(3)
	ds_write_b128 v5, v[22:25]
	s_waitcnt vmcnt(2)
	ds_write_b128 v41, v[26:29]
	s_waitcnt vmcnt(1)
	ds_write_b128 v43, v[30:33]
	s_waitcnt vmcnt(0)
	ds_write_b128 v0, v[34:37]
	s_and_saveexec_b64 s[18:19], vcc
	s_cbranch_execz .LBB0_201
	s_and_b32 s5, s48, 7
	s_mulk_i32 s5, 0x1d1
	v_add_u32_e32 v6, 0xffffff80, v3
	v_lshl_add_u32 v5, v3, 2, s26
	s_mov_b64 s[20:21], 0
	s_branch .LBB0_199
